# attention step: six V-fragment buffers (spare temp quad and the last K-fragment quad added), V fragments prefetched four PV MFMAs ahead
# speedup vs baseline: 1.0065x; 1.0065x over previous
.Lat_loop:
	s_cmp_ge_u32 s46, s45
	s_cbranch_scc1 .Lat_drain
	s_cmp_ge_u32 s46, s78
	s_cbranch_scc1 .Lat_lite_443
	s_lshl_b32 s60, s56, 1
	v_add_u32_e32 v250, s60, v245
	v_mfma_f32_32x32x16_bf16 v[128:143], v[208:211], v[16:19], v[160:175]
	v_add_f32_e32 v247, v247, v96
	v_add_f32_e32 v247, v247, v97
	v_add_f32_e32 v247, v247, v98
	v_add_f32_e32 v247, v247, v99
	v_cvt_pk_bf16_f32 v176, v96, v97
	v_cvt_pk_bf16_f32 v177, v98, v99
	v_mfma_f32_32x32x16_bf16 v[144:159], v[212:215], v[16:19], v[160:175]
	v_add_f32_e32 v247, v247, v100
	v_add_f32_e32 v247, v247, v101
	v_add_f32_e32 v247, v247, v102
	v_add_f32_e32 v247, v247, v103
	v_cvt_pk_bf16_f32 v178, v100, v101
	v_cvt_pk_bf16_f32 v179, v102, v103
	v_mfma_f32_32x32x16_bf16 v[128:143], v[216:219], v[20:23], v[128:143]
	v_add_f32_e32 v247, v247, v104
	v_add_f32_e32 v247, v247, v105
	v_add_f32_e32 v247, v247, v106
	v_add_f32_e32 v247, v247, v107
	v_cvt_pk_bf16_f32 v180, v104, v105
	v_cvt_pk_bf16_f32 v181, v106, v107
	v_mfma_f32_32x32x16_bf16 v[144:159], v[220:223], v[20:23], v[144:159]
	v_add_f32_e32 v247, v247, v108
	v_add_f32_e32 v247, v247, v109
	v_add_f32_e32 v247, v247, v110
	v_add_f32_e32 v247, v247, v111
	v_cvt_pk_bf16_f32 v182, v108, v109
	v_cvt_pk_bf16_f32 v183, v110, v111
	v_mfma_f32_32x32x16_bf16 v[128:143], v[224:227], v[24:27], v[128:143]
	v_add_f32_e32 v247, v247, v112
	v_add_f32_e32 v247, v247, v113
	v_add_f32_e32 v247, v247, v114
	v_add_f32_e32 v247, v247, v115
	v_cvt_pk_bf16_f32 v184, v112, v113
	v_cvt_pk_bf16_f32 v185, v114, v115
	ds_read_b64_tr_b16 v[192:193], v250 offset:0
	ds_read_b64_tr_b16 v[194:195], v250 offset:512
	v_mfma_f32_32x32x16_bf16 v[144:159], v[228:231], v[24:27], v[144:159]
	v_add_f32_e32 v247, v247, v116
	v_add_f32_e32 v247, v247, v117
	v_add_f32_e32 v247, v247, v118
	v_add_f32_e32 v247, v247, v119
	v_cvt_pk_bf16_f32 v186, v116, v117
	v_cvt_pk_bf16_f32 v187, v118, v119
	ds_read_b64_tr_b16 v[196:197], v250 offset:4096
	ds_read_b64_tr_b16 v[198:199], v250 offset:4608
	v_mfma_f32_32x32x16_bf16 v[128:143], v[232:235], v[28:31], v[128:143]
	v_add_f32_e32 v247, v247, v120
	v_add_f32_e32 v247, v247, v121
	v_add_f32_e32 v247, v247, v122
	v_add_f32_e32 v247, v247, v123
	v_cvt_pk_bf16_f32 v188, v120, v121
	v_cvt_pk_bf16_f32 v189, v122, v123
	ds_read_b64_tr_b16 v[200:201], v250 offset:8192
	ds_read_b64_tr_b16 v[202:203], v250 offset:8704
	v_mfma_f32_32x32x16_bf16 v[144:159], v[240:243], v[28:31], v[144:159]
	v_add_f32_e32 v247, v247, v124
	v_add_f32_e32 v247, v247, v125
	v_add_f32_e32 v247, v247, v126
	v_add_f32_e32 v247, v247, v127
	v_cvt_pk_bf16_f32 v190, v124, v125
	v_cvt_pk_bf16_f32 v191, v126, v127
	ds_read_b64_tr_b16 v[204:205], v250 offset:12288
	ds_read_b64_tr_b16 v[206:207], v250 offset:12800
	s_add_i32 m0, s57, s70
	s_nop 0
	global_load_lds_dwordx4 v238, s[74:75]
	s_add_u32 s74, s74, 0x10000
	s_addc_u32 s75, s75, 0
	s_lshl_b32 s60, s58, 1
	s_add_i32 s60, s60, s71
	s_mov_b32 m0, s60
	s_nop 0
	global_load_lds_dwordx4 v239, s[76:77]
	s_add_u32 s62, s76, 0x80
	s_addc_u32 s63, s77, 0
	s_add_i32 m0, s60, 0x2000
	s_nop 0
	global_load_lds_dwordx4 v239, s[62:63]
	s_add_u32 s76, s76, 0x10000
	s_addc_u32 s77, s77, 0
	s_cmp_lg_u32 s46, s79
	s_cbranch_scc1 .Lat_nomask_530
	s_sub_u32 s60, s46, s72
	s_lshl_b32 s60, s60, 6
	v_lshl_add_u32 v0, v252, 2, s60
	v_sub_u32_e32 v0, v246, v0
	v_mov_b32_e32 v1, 0xff800000
	v_cmp_gt_i32_e64 s[60:61], 0, v0
	v_cmp_gt_i32_e64 s[62:63], 32, v0
	v_cmp_gt_i32_e64 s[64:65], 1, v0
	v_cmp_gt_i32_e64 s[66:67], 33, v0
	v_cndmask_b32_e64 v128, v128, v1, s[60:61]
	v_cmp_gt_i32_e64 s[60:61], 2, v0
	v_cndmask_b32_e64 v144, v144, v1, s[62:63]
	v_cmp_gt_i32_e64 s[62:63], 34, v0
	v_cndmask_b32_e64 v129, v129, v1, s[64:65]
	v_cmp_gt_i32_e64 s[64:65], 3, v0
	v_cndmask_b32_e64 v145, v145, v1, s[66:67]
	v_cmp_gt_i32_e64 s[66:67], 35, v0
	v_cndmask_b32_e64 v130, v130, v1, s[60:61]
	v_cmp_gt_i32_e64 s[60:61], 8, v0
	v_cndmask_b32_e64 v146, v146, v1, s[62:63]
	v_cmp_gt_i32_e64 s[62:63], 40, v0
	v_cndmask_b32_e64 v131, v131, v1, s[64:65]
	v_cmp_gt_i32_e64 s[64:65], 9, v0
	v_cndmask_b32_e64 v147, v147, v1, s[66:67]
	v_cmp_gt_i32_e64 s[66:67], 41, v0
	v_cndmask_b32_e64 v132, v132, v1, s[60:61]
	v_cmp_gt_i32_e64 s[60:61], 10, v0
	v_cndmask_b32_e64 v148, v148, v1, s[62:63]
	v_cmp_gt_i32_e64 s[62:63], 42, v0
	v_cndmask_b32_e64 v133, v133, v1, s[64:65]
	v_cmp_gt_i32_e64 s[64:65], 11, v0
	v_cndmask_b32_e64 v149, v149, v1, s[66:67]
	v_cmp_gt_i32_e64 s[66:67], 43, v0
	v_cndmask_b32_e64 v134, v134, v1, s[60:61]
	v_cmp_gt_i32_e64 s[60:61], 16, v0
	v_cndmask_b32_e64 v150, v150, v1, s[62:63]
	v_cmp_gt_i32_e64 s[62:63], 48, v0
	v_cndmask_b32_e64 v135, v135, v1, s[64:65]
	v_cmp_gt_i32_e64 s[64:65], 17, v0
	v_cndmask_b32_e64 v151, v151, v1, s[66:67]
	v_cmp_gt_i32_e64 s[66:67], 49, v0
	v_cndmask_b32_e64 v136, v136, v1, s[60:61]
	v_cmp_gt_i32_e64 s[60:61], 18, v0
	v_cndmask_b32_e64 v152, v152, v1, s[62:63]
	v_cmp_gt_i32_e64 s[62:63], 50, v0
	v_cndmask_b32_e64 v137, v137, v1, s[64:65]
	v_cmp_gt_i32_e64 s[64:65], 19, v0
	v_cndmask_b32_e64 v153, v153, v1, s[66:67]
	v_cmp_gt_i32_e64 s[66:67], 51, v0
	v_cndmask_b32_e64 v138, v138, v1, s[60:61]
	v_cmp_gt_i32_e64 s[60:61], 24, v0
	v_cndmask_b32_e64 v154, v154, v1, s[62:63]
	v_cmp_gt_i32_e64 s[62:63], 56, v0
	v_cndmask_b32_e64 v139, v139, v1, s[64:65]
	v_cmp_gt_i32_e64 s[64:65], 25, v0
	v_cndmask_b32_e64 v155, v155, v1, s[66:67]
	v_cmp_gt_i32_e64 s[66:67], 57, v0
	v_cndmask_b32_e64 v140, v140, v1, s[60:61]
	v_cmp_gt_i32_e64 s[60:61], 26, v0
	v_cndmask_b32_e64 v156, v156, v1, s[62:63]
	v_cmp_gt_i32_e64 s[62:63], 58, v0
	v_cndmask_b32_e64 v141, v141, v1, s[64:65]
	v_cmp_gt_i32_e64 s[64:65], 27, v0
	v_cndmask_b32_e64 v157, v157, v1, s[66:67]
	v_cmp_gt_i32_e64 s[66:67], 59, v0
	v_cndmask_b32_e64 v142, v142, v1, s[60:61]
	s_nop 1
	v_cndmask_b32_e64 v158, v158, v1, s[62:63]
	v_cndmask_b32_e64 v143, v143, v1, s[64:65]
	v_cndmask_b32_e64 v159, v159, v1, s[66:67]
.Lat_nomask_530:
	ds_read_b64_tr_b16 v[12:13], v250 offset:1024
	ds_read_b64_tr_b16 v[14:15], v250 offset:1536
	s_waitcnt lgkmcnt(8)
	v_mfma_f32_32x32x16_bf16 v[32:47], v[176:179], v[192:195], v[32:47]
	v_max3_f32 v2, v128, v129, v144
	v_max3_f32 v4, v130, v131, v145
	v_max3_f32 v2, v2, v146, v147
	ds_read_b64_tr_b16 v[240:241], v250 offset:5120
	ds_read_b64_tr_b16 v[242:243], v250 offset:5632
	s_waitcnt lgkmcnt(8)
	v_mfma_f32_32x32x16_bf16 v[48:63], v[176:179], v[196:199], v[48:63]
	v_max3_f32 v2, v2, v132, v133
	v_max3_f32 v4, v4, v134, v135
	v_max3_f32 v2, v2, v148, v149
	ds_read_b64_tr_b16 v[192:193], v250 offset:9216
	ds_read_b64_tr_b16 v[194:195], v250 offset:9728
	s_waitcnt lgkmcnt(8)
	v_mfma_f32_32x32x16_bf16 v[64:79], v[176:179], v[200:203], v[64:79]
	v_max3_f32 v4, v4, v150, v151
	v_max3_f32 v2, v2, v136, v137
	v_max3_f32 v4, v4, v138, v139
	ds_read_b64_tr_b16 v[196:197], v250 offset:13312
	ds_read_b64_tr_b16 v[198:199], v250 offset:13824
	s_waitcnt lgkmcnt(8)
	v_mfma_f32_32x32x16_bf16 v[80:95], v[176:179], v[204:207], v[80:95]
	v_max3_f32 v2, v2, v152, v153
	v_max3_f32 v4, v4, v154, v155
	v_max3_f32 v2, v2, v140, v141
	ds_read_b64_tr_b16 v[200:201], v250 offset:2048
	ds_read_b64_tr_b16 v[202:203], v250 offset:2560
	s_waitcnt lgkmcnt(8)
	v_mfma_f32_32x32x16_bf16 v[32:47], v[180:183], v[12:15], v[32:47]
	v_max3_f32 v4, v4, v142, v143
	v_max3_f32 v2, v2, v156, v157
	v_max3_f32 v4, v4, v158, v159
	ds_read_b64_tr_b16 v[204:205], v250 offset:6144
	ds_read_b64_tr_b16 v[206:207], v250 offset:6656
	s_waitcnt lgkmcnt(8)
	v_mfma_f32_32x32x16_bf16 v[48:63], v[180:183], v[240:243], v[48:63]
	v_max_f32_e32 v2, v2, v4
	v_mov_b32_e32 v4, v2
	s_nop 1
	v_permlane32_swap_b32_e32 v2, v4
	v_max_f32_e32 v2, v2, v4
	v_mov_b32_e32 v5, 0x41400000
	v_cmp_gt_f32_e32 vcc, v2, v5
	s_mov_b64 s[68:69], vcc
	s_cmp_lg_u64 vcc, 0
	s_cbranch_scc0 .Lat_noresc_443
	v_max_f32_e32 v4, 0, v2
	v_add_f32_e32 v248, v248, v4
	v_sub_f32_e32 v128, v128, v4
	v_sub_f32_e32 v129, v129, v4
	v_sub_f32_e32 v130, v130, v4
	v_sub_f32_e32 v131, v131, v4
	v_sub_f32_e32 v132, v132, v4
	v_sub_f32_e32 v133, v133, v4
	v_sub_f32_e32 v134, v134, v4
	v_sub_f32_e32 v135, v135, v4
	v_sub_f32_e32 v136, v136, v4
	v_sub_f32_e32 v137, v137, v4
	v_sub_f32_e32 v138, v138, v4
	v_sub_f32_e32 v139, v139, v4
	v_sub_f32_e32 v140, v140, v4
	v_sub_f32_e32 v141, v141, v4
	v_sub_f32_e32 v142, v142, v4
	v_sub_f32_e32 v143, v143, v4
	v_sub_f32_e32 v144, v144, v4
	v_sub_f32_e32 v145, v145, v4
	v_sub_f32_e32 v146, v146, v4
	v_sub_f32_e32 v147, v147, v4
	v_sub_f32_e32 v148, v148, v4
	v_sub_f32_e32 v149, v149, v4
	v_sub_f32_e32 v150, v150, v4
	v_sub_f32_e32 v151, v151, v4
	v_sub_f32_e32 v152, v152, v4
	v_sub_f32_e32 v153, v153, v4
	v_sub_f32_e32 v154, v154, v4
	v_sub_f32_e32 v155, v155, v4
	v_sub_f32_e32 v156, v156, v4
	v_sub_f32_e32 v157, v157, v4
	v_sub_f32_e32 v158, v158, v4
	v_sub_f32_e32 v159, v159, v4
	v_xor_b32_e32 v5, 0x80000000, v248
	v_mov_b32_e32 v160, v5
	v_mov_b32_e32 v161, v5
	v_mov_b32_e32 v162, v5
	v_mov_b32_e32 v163, v5
	v_mov_b32_e32 v164, v5
	v_mov_b32_e32 v165, v5
	v_mov_b32_e32 v166, v5
	v_mov_b32_e32 v167, v5
	v_mov_b32_e32 v168, v5
	v_mov_b32_e32 v169, v5
	v_mov_b32_e32 v170, v5
	v_mov_b32_e32 v171, v5
	v_mov_b32_e32 v172, v5
	v_mov_b32_e32 v173, v5
	v_mov_b32_e32 v174, v5
	v_mov_b32_e32 v175, v5
	v_xor_b32_e32 v6, 0x80000000, v4
	v_exp_f32_e32 v6, v6
	s_nop 0
	v_mul_f32_e32 v247, v247, v6
	v_and_b32_e32 v7, 31, v237
	v_lshl_add_u32 v7, v7, 2, v249
	v_cmp_eq_u32_e32 vcc, 0, v252
	s_and_saveexec_b64 s[60:61], vcc
	ds_write_b32 v7, v6
	s_or_b64 exec, exec, s[60:61]
.Lat_noresc_443:
	v_add_u32_e32 v3, s58, v244
	ds_read_b64_tr_b16 v[12:13], v250 offset:10240
	ds_read_b64_tr_b16 v[14:15], v250 offset:10752
	s_waitcnt lgkmcnt(8)
	v_mfma_f32_32x32x16_bf16 v[64:79], v[180:183], v[192:195], v[64:79]
	v_exp_f32_e32 v128, v128
	v_exp_f32_e32 v129, v129
	v_exp_f32_e32 v130, v130
	ds_read_b128 v[208:211], v3
	ds_read_b64_tr_b16 v[240:241], v250 offset:14336
	ds_read_b64_tr_b16 v[242:243], v250 offset:14848
	s_waitcnt lgkmcnt(9)
	v_mfma_f32_32x32x16_bf16 v[80:95], v[180:183], v[196:199], v[80:95]
	v_exp_f32_e32 v131, v131
	v_exp_f32_e32 v132, v132
	v_exp_f32_e32 v133, v133
	ds_read_b128 v[212:215], v3 offset:512
	ds_read_b64_tr_b16 v[192:193], v250 offset:3072
	ds_read_b64_tr_b16 v[194:195], v250 offset:3584
	s_waitcnt lgkmcnt(10)
	v_mfma_f32_32x32x16_bf16 v[32:47], v[184:187], v[200:203], v[32:47]
	v_exp_f32_e32 v134, v134
	v_exp_f32_e32 v135, v135
	v_exp_f32_e32 v136, v136
	ds_read_b128 v[216:219], v3 offset:2048
	ds_read_b64_tr_b16 v[196:197], v250 offset:7168
	ds_read_b64_tr_b16 v[198:199], v250 offset:7680
	s_waitcnt lgkmcnt(11)
	v_mfma_f32_32x32x16_bf16 v[48:63], v[184:187], v[204:207], v[48:63]
	v_exp_f32_e32 v137, v137
	v_exp_f32_e32 v138, v138
	v_exp_f32_e32 v139, v139
	ds_read_b128 v[220:223], v3 offset:2560
	ds_read_b64_tr_b16 v[200:201], v250 offset:11264
	ds_read_b64_tr_b16 v[202:203], v250 offset:11776
	s_waitcnt lgkmcnt(12)
	v_mfma_f32_32x32x16_bf16 v[64:79], v[184:187], v[12:15], v[64:79]
	v_exp_f32_e32 v140, v140
	v_exp_f32_e32 v141, v141
	v_exp_f32_e32 v142, v142
	ds_read_b128 v[224:227], v3 offset:4096
	ds_read_b64_tr_b16 v[204:205], v250 offset:15360
	ds_read_b64_tr_b16 v[206:207], v250 offset:15872
	s_waitcnt lgkmcnt(12)
	v_mfma_f32_32x32x16_bf16 v[80:95], v[184:187], v[240:243], v[80:95]
	v_exp_f32_e32 v143, v143
	v_exp_f32_e32 v144, v144
	v_exp_f32_e32 v145, v145
	ds_read_b128 v[228:231], v3 offset:4608
	s_waitcnt lgkmcnt(10)
	v_mfma_f32_32x32x16_bf16 v[32:47], v[188:191], v[192:195], v[32:47]
	v_exp_f32_e32 v146, v146
	v_exp_f32_e32 v147, v147
	v_exp_f32_e32 v148, v148
	ds_read_b128 v[232:235], v3 offset:6144
	s_waitcnt lgkmcnt(8)
	v_mfma_f32_32x32x16_bf16 v[48:63], v[188:191], v[196:199], v[48:63]
	v_exp_f32_e32 v149, v149
	v_exp_f32_e32 v150, v150
	v_exp_f32_e32 v151, v151
	ds_read_b128 v[240:243], v3 offset:6656
	s_waitcnt lgkmcnt(6)
	v_mfma_f32_32x32x16_bf16 v[64:79], v[188:191], v[200:203], v[64:79]
	v_exp_f32_e32 v152, v152
	v_exp_f32_e32 v153, v153
	v_exp_f32_e32 v154, v154
	v_exp_f32_e32 v155, v155
	s_waitcnt lgkmcnt(3)
	v_mfma_f32_32x32x16_bf16 v[80:95], v[188:191], v[204:207], v[80:95]
	v_exp_f32_e32 v156, v156
	v_exp_f32_e32 v157, v157
	v_exp_f32_e32 v158, v158
	v_exp_f32_e32 v159, v159
	s_mov_b32 s67, s56
	s_mov_b32 s56, s57
	s_mov_b32 s57, s58
	s_mov_b32 s58, s67
	s_add_u32 s46, s46, 1
	s_waitcnt vmcnt(3) lgkmcnt(0)
	s_barrier
	s_cmp_lg_u64 s[68:69], 0
	s_cbranch_scc0 .Lat_norescO_443
	v_lshl_add_u32 v250, v252, 4, v249
	ds_read_b128 v[0:3], v250 offset:0
	ds_read_b128 v[4:7], v250 offset:32
	ds_read_b128 v[8:11], v250 offset:64
	ds_read_b128 v[12:15], v250 offset:96
	s_nop 7
	s_nop 7
	s_waitcnt lgkmcnt(0)
	v_mul_f32_e32 v32, v32, v0
	v_mul_f32_e32 v33, v33, v1
	v_mul_f32_e32 v34, v34, v2
	v_mul_f32_e32 v35, v35, v3
	v_mul_f32_e32 v36, v36, v4
	v_mul_f32_e32 v37, v37, v5
	v_mul_f32_e32 v38, v38, v6
	v_mul_f32_e32 v39, v39, v7
	v_mul_f32_e32 v40, v40, v8
	v_mul_f32_e32 v41, v41, v9
	v_mul_f32_e32 v42, v42, v10
	v_mul_f32_e32 v43, v43, v11
	v_mul_f32_e32 v44, v44, v12
	v_mul_f32_e32 v45, v45, v13
	v_mul_f32_e32 v46, v46, v14
	v_mul_f32_e32 v47, v47, v15
	v_mul_f32_e32 v48, v48, v0
	v_mul_f32_e32 v49, v49, v1
	v_mul_f32_e32 v50, v50, v2
	v_mul_f32_e32 v51, v51, v3
	v_mul_f32_e32 v52, v52, v4
	v_mul_f32_e32 v53, v53, v5
	v_mul_f32_e32 v54, v54, v6
	v_mul_f32_e32 v55, v55, v7
	v_mul_f32_e32 v56, v56, v8
	v_mul_f32_e32 v57, v57, v9
	v_mul_f32_e32 v58, v58, v10
	v_mul_f32_e32 v59, v59, v11
	v_mul_f32_e32 v60, v60, v12
	v_mul_f32_e32 v61, v61, v13
	v_mul_f32_e32 v62, v62, v14
	v_mul_f32_e32 v63, v63, v15
	v_mul_f32_e32 v64, v64, v0
	v_mul_f32_e32 v65, v65, v1
	v_mul_f32_e32 v66, v66, v2
	v_mul_f32_e32 v67, v67, v3
	v_mul_f32_e32 v68, v68, v4
	v_mul_f32_e32 v69, v69, v5
	v_mul_f32_e32 v70, v70, v6
	v_mul_f32_e32 v71, v71, v7
	v_mul_f32_e32 v72, v72, v8
	v_mul_f32_e32 v73, v73, v9
	v_mul_f32_e32 v74, v74, v10
	v_mul_f32_e32 v75, v75, v11
	v_mul_f32_e32 v76, v76, v12
	v_mul_f32_e32 v77, v77, v13
	v_mul_f32_e32 v78, v78, v14
	v_mul_f32_e32 v79, v79, v15
	v_mul_f32_e32 v80, v80, v0
	v_mul_f32_e32 v81, v81, v1
	v_mul_f32_e32 v82, v82, v2
	v_mul_f32_e32 v83, v83, v3
	v_mul_f32_e32 v84, v84, v4
	v_mul_f32_e32 v85, v85, v5
	v_mul_f32_e32 v86, v86, v6
	v_mul_f32_e32 v87, v87, v7
	v_mul_f32_e32 v88, v88, v8
	v_mul_f32_e32 v89, v89, v9
	v_mul_f32_e32 v90, v90, v10
	v_mul_f32_e32 v91, v91, v11
	v_mul_f32_e32 v92, v92, v12
	v_mul_f32_e32 v93, v93, v13
	v_mul_f32_e32 v94, v94, v14
	v_mul_f32_e32 v95, v95, v15
.Lat_norescO_443:
.Lat_next_443:
	s_cmp_ge_u32 s46, s45
	s_cbranch_scc1 .Lat_drain
	s_cmp_ge_u32 s46, s78
	s_cbranch_scc1 .Lat_lite_870
	s_lshl_b32 s60, s56, 1
	v_add_u32_e32 v250, s60, v245
	v_mfma_f32_32x32x16_bf16 v[96:111], v[208:211], v[16:19], v[160:175]
	v_add_f32_e32 v247, v247, v128
	v_add_f32_e32 v247, v247, v129
	v_add_f32_e32 v247, v247, v130
	v_add_f32_e32 v247, v247, v131
	v_cvt_pk_bf16_f32 v176, v128, v129
	v_cvt_pk_bf16_f32 v177, v130, v131
	v_mfma_f32_32x32x16_bf16 v[112:127], v[212:215], v[16:19], v[160:175]
	v_add_f32_e32 v247, v247, v132
	v_add_f32_e32 v247, v247, v133
	v_add_f32_e32 v247, v247, v134
	v_add_f32_e32 v247, v247, v135
	v_cvt_pk_bf16_f32 v178, v132, v133
	v_cvt_pk_bf16_f32 v179, v134, v135
	v_mfma_f32_32x32x16_bf16 v[96:111], v[216:219], v[20:23], v[96:111]
	v_add_f32_e32 v247, v247, v136
	v_add_f32_e32 v247, v247, v137
	v_add_f32_e32 v247, v247, v138
	v_add_f32_e32 v247, v247, v139
	v_cvt_pk_bf16_f32 v180, v136, v137
	v_cvt_pk_bf16_f32 v181, v138, v139
	v_mfma_f32_32x32x16_bf16 v[112:127], v[220:223], v[20:23], v[112:127]
	v_add_f32_e32 v247, v247, v140
	v_add_f32_e32 v247, v247, v141
	v_add_f32_e32 v247, v247, v142
	v_add_f32_e32 v247, v247, v143
	v_cvt_pk_bf16_f32 v182, v140, v141
	v_cvt_pk_bf16_f32 v183, v142, v143
	v_mfma_f32_32x32x16_bf16 v[96:111], v[224:227], v[24:27], v[96:111]
	v_add_f32_e32 v247, v247, v144
	v_add_f32_e32 v247, v247, v145
	v_add_f32_e32 v247, v247, v146
	v_add_f32_e32 v247, v247, v147
	v_cvt_pk_bf16_f32 v184, v144, v145
	v_cvt_pk_bf16_f32 v185, v146, v147
	ds_read_b64_tr_b16 v[192:193], v250 offset:0
	ds_read_b64_tr_b16 v[194:195], v250 offset:512
	v_mfma_f32_32x32x16_bf16 v[112:127], v[228:231], v[24:27], v[112:127]
	v_add_f32_e32 v247, v247, v148
	v_add_f32_e32 v247, v247, v149
	v_add_f32_e32 v247, v247, v150
	v_add_f32_e32 v247, v247, v151
	v_cvt_pk_bf16_f32 v186, v148, v149
	v_cvt_pk_bf16_f32 v187, v150, v151
	ds_read_b64_tr_b16 v[196:197], v250 offset:4096
	ds_read_b64_tr_b16 v[198:199], v250 offset:4608
	v_mfma_f32_32x32x16_bf16 v[96:111], v[232:235], v[28:31], v[96:111]
	v_add_f32_e32 v247, v247, v152
	v_add_f32_e32 v247, v247, v153
	v_add_f32_e32 v247, v247, v154
	v_add_f32_e32 v247, v247, v155
	v_cvt_pk_bf16_f32 v188, v152, v153
	v_cvt_pk_bf16_f32 v189, v154, v155
	ds_read_b64_tr_b16 v[200:201], v250 offset:8192
	ds_read_b64_tr_b16 v[202:203], v250 offset:8704
	v_mfma_f32_32x32x16_bf16 v[112:127], v[240:243], v[28:31], v[112:127]
	v_add_f32_e32 v247, v247, v156
	v_add_f32_e32 v247, v247, v157
	v_add_f32_e32 v247, v247, v158
	v_add_f32_e32 v247, v247, v159
	v_cvt_pk_bf16_f32 v190, v156, v157
	v_cvt_pk_bf16_f32 v191, v158, v159
	ds_read_b64_tr_b16 v[204:205], v250 offset:12288
	ds_read_b64_tr_b16 v[206:207], v250 offset:12800
	s_add_i32 m0, s57, s70
	s_nop 0
	global_load_lds_dwordx4 v238, s[74:75]
	s_add_u32 s74, s74, 0x10000
	s_addc_u32 s75, s75, 0
	s_lshl_b32 s60, s58, 1
	s_add_i32 s60, s60, s71
	s_mov_b32 m0, s60
	s_nop 0
	global_load_lds_dwordx4 v239, s[76:77]
	s_add_u32 s62, s76, 0x80
	s_addc_u32 s63, s77, 0
	s_add_i32 m0, s60, 0x2000
	s_nop 0
	global_load_lds_dwordx4 v239, s[62:63]
	s_add_u32 s76, s76, 0x10000
	s_addc_u32 s77, s77, 0
	s_cmp_lg_u32 s46, s79
	s_cbranch_scc1 .Lat_nomask_957
	s_sub_u32 s60, s46, s72
	s_lshl_b32 s60, s60, 6
	v_lshl_add_u32 v0, v252, 2, s60
	v_sub_u32_e32 v0, v246, v0
	v_mov_b32_e32 v1, 0xff800000
	v_cmp_gt_i32_e64 s[60:61], 0, v0
	v_cmp_gt_i32_e64 s[62:63], 32, v0
	v_cmp_gt_i32_e64 s[64:65], 1, v0
	v_cmp_gt_i32_e64 s[66:67], 33, v0
	v_cndmask_b32_e64 v96, v96, v1, s[60:61]
	v_cmp_gt_i32_e64 s[60:61], 2, v0
	v_cndmask_b32_e64 v112, v112, v1, s[62:63]
	v_cmp_gt_i32_e64 s[62:63], 34, v0
	v_cndmask_b32_e64 v97, v97, v1, s[64:65]
	v_cmp_gt_i32_e64 s[64:65], 3, v0
	v_cndmask_b32_e64 v113, v113, v1, s[66:67]
	v_cmp_gt_i32_e64 s[66:67], 35, v0
	v_cndmask_b32_e64 v98, v98, v1, s[60:61]
	v_cmp_gt_i32_e64 s[60:61], 8, v0
	v_cndmask_b32_e64 v114, v114, v1, s[62:63]
	v_cmp_gt_i32_e64 s[62:63], 40, v0
	v_cndmask_b32_e64 v99, v99, v1, s[64:65]
	v_cmp_gt_i32_e64 s[64:65], 9, v0
	v_cndmask_b32_e64 v115, v115, v1, s[66:67]
	v_cmp_gt_i32_e64 s[66:67], 41, v0
	v_cndmask_b32_e64 v100, v100, v1, s[60:61]
	v_cmp_gt_i32_e64 s[60:61], 10, v0
	v_cndmask_b32_e64 v116, v116, v1, s[62:63]
	v_cmp_gt_i32_e64 s[62:63], 42, v0
	v_cndmask_b32_e64 v101, v101, v1, s[64:65]
	v_cmp_gt_i32_e64 s[64:65], 11, v0
	v_cndmask_b32_e64 v117, v117, v1, s[66:67]
	v_cmp_gt_i32_e64 s[66:67], 43, v0
	v_cndmask_b32_e64 v102, v102, v1, s[60:61]
	v_cmp_gt_i32_e64 s[60:61], 16, v0
	v_cndmask_b32_e64 v118, v118, v1, s[62:63]
	v_cmp_gt_i32_e64 s[62:63], 48, v0
	v_cndmask_b32_e64 v103, v103, v1, s[64:65]
	v_cmp_gt_i32_e64 s[64:65], 17, v0
	v_cndmask_b32_e64 v119, v119, v1, s[66:67]
	v_cmp_gt_i32_e64 s[66:67], 49, v0
	v_cndmask_b32_e64 v104, v104, v1, s[60:61]
	v_cmp_gt_i32_e64 s[60:61], 18, v0
	v_cndmask_b32_e64 v120, v120, v1, s[62:63]
	v_cmp_gt_i32_e64 s[62:63], 50, v0
	v_cndmask_b32_e64 v105, v105, v1, s[64:65]
	v_cmp_gt_i32_e64 s[64:65], 19, v0
	v_cndmask_b32_e64 v121, v121, v1, s[66:67]
	v_cmp_gt_i32_e64 s[66:67], 51, v0
	v_cndmask_b32_e64 v106, v106, v1, s[60:61]
	v_cmp_gt_i32_e64 s[60:61], 24, v0
	v_cndmask_b32_e64 v122, v122, v1, s[62:63]
	v_cmp_gt_i32_e64 s[62:63], 56, v0
	v_cndmask_b32_e64 v107, v107, v1, s[64:65]
	v_cmp_gt_i32_e64 s[64:65], 25, v0
	v_cndmask_b32_e64 v123, v123, v1, s[66:67]
	v_cmp_gt_i32_e64 s[66:67], 57, v0
	v_cndmask_b32_e64 v108, v108, v1, s[60:61]
	v_cmp_gt_i32_e64 s[60:61], 26, v0
	v_cndmask_b32_e64 v124, v124, v1, s[62:63]
	v_cmp_gt_i32_e64 s[62:63], 58, v0
	v_cndmask_b32_e64 v109, v109, v1, s[64:65]
	v_cmp_gt_i32_e64 s[64:65], 27, v0
	v_cndmask_b32_e64 v125, v125, v1, s[66:67]
	v_cmp_gt_i32_e64 s[66:67], 59, v0
	v_cndmask_b32_e64 v110, v110, v1, s[60:61]
	s_nop 1
	v_cndmask_b32_e64 v126, v126, v1, s[62:63]
	v_cndmask_b32_e64 v111, v111, v1, s[64:65]
	v_cndmask_b32_e64 v127, v127, v1, s[66:67]
.Lat_nomask_957:
	ds_read_b64_tr_b16 v[12:13], v250 offset:1024
	ds_read_b64_tr_b16 v[14:15], v250 offset:1536
	s_waitcnt lgkmcnt(8)
	v_mfma_f32_32x32x16_bf16 v[32:47], v[176:179], v[192:195], v[32:47]
	v_max3_f32 v2, v96, v97, v112
	v_max3_f32 v4, v98, v99, v113
	v_max3_f32 v2, v2, v114, v115
	ds_read_b64_tr_b16 v[240:241], v250 offset:5120
	ds_read_b64_tr_b16 v[242:243], v250 offset:5632
	s_waitcnt lgkmcnt(8)
	v_mfma_f32_32x32x16_bf16 v[48:63], v[176:179], v[196:199], v[48:63]
	v_max3_f32 v2, v2, v100, v101
	v_max3_f32 v4, v4, v102, v103
	v_max3_f32 v2, v2, v116, v117
	ds_read_b64_tr_b16 v[192:193], v250 offset:9216
	ds_read_b64_tr_b16 v[194:195], v250 offset:9728
	s_waitcnt lgkmcnt(8)
	v_mfma_f32_32x32x16_bf16 v[64:79], v[176:179], v[200:203], v[64:79]
	v_max3_f32 v4, v4, v118, v119
	v_max3_f32 v2, v2, v104, v105
	v_max3_f32 v4, v4, v106, v107
	ds_read_b64_tr_b16 v[196:197], v250 offset:13312
	ds_read_b64_tr_b16 v[198:199], v250 offset:13824
	s_waitcnt lgkmcnt(8)
	v_mfma_f32_32x32x16_bf16 v[80:95], v[176:179], v[204:207], v[80:95]
	v_max3_f32 v2, v2, v120, v121
	v_max3_f32 v4, v4, v122, v123
	v_max3_f32 v2, v2, v108, v109
	ds_read_b64_tr_b16 v[200:201], v250 offset:2048
	ds_read_b64_tr_b16 v[202:203], v250 offset:2560
	s_waitcnt lgkmcnt(8)
	v_mfma_f32_32x32x16_bf16 v[32:47], v[180:183], v[12:15], v[32:47]
	v_max3_f32 v4, v4, v110, v111
	v_max3_f32 v2, v2, v124, v125
	v_max3_f32 v4, v4, v126, v127
	ds_read_b64_tr_b16 v[204:205], v250 offset:6144
	ds_read_b64_tr_b16 v[206:207], v250 offset:6656
	s_waitcnt lgkmcnt(8)
	v_mfma_f32_32x32x16_bf16 v[48:63], v[180:183], v[240:243], v[48:63]
	v_max_f32_e32 v2, v2, v4
	v_mov_b32_e32 v4, v2
	s_nop 1
	v_permlane32_swap_b32_e32 v2, v4
	v_max_f32_e32 v2, v2, v4
	v_mov_b32_e32 v5, 0x41400000
	v_cmp_gt_f32_e32 vcc, v2, v5
	s_mov_b64 s[68:69], vcc
	s_cmp_lg_u64 vcc, 0
	s_cbranch_scc0 .Lat_noresc_870
	v_max_f32_e32 v4, 0, v2
	v_add_f32_e32 v248, v248, v4
	v_sub_f32_e32 v96, v96, v4
	v_sub_f32_e32 v97, v97, v4
	v_sub_f32_e32 v98, v98, v4
	v_sub_f32_e32 v99, v99, v4
	v_sub_f32_e32 v100, v100, v4
	v_sub_f32_e32 v101, v101, v4
	v_sub_f32_e32 v102, v102, v4
	v_sub_f32_e32 v103, v103, v4
	v_sub_f32_e32 v104, v104, v4
	v_sub_f32_e32 v105, v105, v4
	v_sub_f32_e32 v106, v106, v4
	v_sub_f32_e32 v107, v107, v4
	v_sub_f32_e32 v108, v108, v4
	v_sub_f32_e32 v109, v109, v4
	v_sub_f32_e32 v110, v110, v4
	v_sub_f32_e32 v111, v111, v4
	v_sub_f32_e32 v112, v112, v4
	v_sub_f32_e32 v113, v113, v4
	v_sub_f32_e32 v114, v114, v4
	v_sub_f32_e32 v115, v115, v4
	v_sub_f32_e32 v116, v116, v4
	v_sub_f32_e32 v117, v117, v4
	v_sub_f32_e32 v118, v118, v4
	v_sub_f32_e32 v119, v119, v4
	v_sub_f32_e32 v120, v120, v4
	v_sub_f32_e32 v121, v121, v4
	v_sub_f32_e32 v122, v122, v4
	v_sub_f32_e32 v123, v123, v4
	v_sub_f32_e32 v124, v124, v4
	v_sub_f32_e32 v125, v125, v4
	v_sub_f32_e32 v126, v126, v4
	v_sub_f32_e32 v127, v127, v4
	v_xor_b32_e32 v5, 0x80000000, v248
	v_mov_b32_e32 v160, v5
	v_mov_b32_e32 v161, v5
	v_mov_b32_e32 v162, v5
	v_mov_b32_e32 v163, v5
	v_mov_b32_e32 v164, v5
	v_mov_b32_e32 v165, v5
	v_mov_b32_e32 v166, v5
	v_mov_b32_e32 v167, v5
	v_mov_b32_e32 v168, v5
	v_mov_b32_e32 v169, v5
	v_mov_b32_e32 v170, v5
	v_mov_b32_e32 v171, v5
	v_mov_b32_e32 v172, v5
	v_mov_b32_e32 v173, v5
	v_mov_b32_e32 v174, v5
	v_mov_b32_e32 v175, v5
	v_xor_b32_e32 v6, 0x80000000, v4
	v_exp_f32_e32 v6, v6
	s_nop 0
	v_mul_f32_e32 v247, v247, v6
	v_and_b32_e32 v7, 31, v237
	v_lshl_add_u32 v7, v7, 2, v249
	v_cmp_eq_u32_e32 vcc, 0, v252
	s_and_saveexec_b64 s[60:61], vcc
	ds_write_b32 v7, v6
	s_or_b64 exec, exec, s[60:61]
.Lat_noresc_870:
	v_add_u32_e32 v3, s58, v244
	ds_read_b64_tr_b16 v[12:13], v250 offset:10240
	ds_read_b64_tr_b16 v[14:15], v250 offset:10752
	s_waitcnt lgkmcnt(8)
	v_mfma_f32_32x32x16_bf16 v[64:79], v[180:183], v[192:195], v[64:79]
	v_exp_f32_e32 v96, v96
	v_exp_f32_e32 v97, v97
	v_exp_f32_e32 v98, v98
	ds_read_b128 v[208:211], v3
	ds_read_b64_tr_b16 v[240:241], v250 offset:14336
	ds_read_b64_tr_b16 v[242:243], v250 offset:14848
	s_waitcnt lgkmcnt(9)
	v_mfma_f32_32x32x16_bf16 v[80:95], v[180:183], v[196:199], v[80:95]
	v_exp_f32_e32 v99, v99
	v_exp_f32_e32 v100, v100
	v_exp_f32_e32 v101, v101
	ds_read_b128 v[212:215], v3 offset:512
	ds_read_b64_tr_b16 v[192:193], v250 offset:3072
	ds_read_b64_tr_b16 v[194:195], v250 offset:3584
	s_waitcnt lgkmcnt(10)
	v_mfma_f32_32x32x16_bf16 v[32:47], v[184:187], v[200:203], v[32:47]
	v_exp_f32_e32 v102, v102
	v_exp_f32_e32 v103, v103
	v_exp_f32_e32 v104, v104
	ds_read_b128 v[216:219], v3 offset:2048
	ds_read_b64_tr_b16 v[196:197], v250 offset:7168
	ds_read_b64_tr_b16 v[198:199], v250 offset:7680
	s_waitcnt lgkmcnt(11)
	v_mfma_f32_32x32x16_bf16 v[48:63], v[184:187], v[204:207], v[48:63]
	v_exp_f32_e32 v105, v105
	v_exp_f32_e32 v106, v106
	v_exp_f32_e32 v107, v107
	ds_read_b128 v[220:223], v3 offset:2560
	ds_read_b64_tr_b16 v[200:201], v250 offset:11264
	ds_read_b64_tr_b16 v[202:203], v250 offset:11776
	s_waitcnt lgkmcnt(12)
	v_mfma_f32_32x32x16_bf16 v[64:79], v[184:187], v[12:15], v[64:79]
	v_exp_f32_e32 v108, v108
	v_exp_f32_e32 v109, v109
	v_exp_f32_e32 v110, v110
	ds_read_b128 v[224:227], v3 offset:4096
	ds_read_b64_tr_b16 v[204:205], v250 offset:15360
	ds_read_b64_tr_b16 v[206:207], v250 offset:15872
	s_waitcnt lgkmcnt(12)
	v_mfma_f32_32x32x16_bf16 v[80:95], v[184:187], v[240:243], v[80:95]
	v_exp_f32_e32 v111, v111
	v_exp_f32_e32 v112, v112
	v_exp_f32_e32 v113, v113
	ds_read_b128 v[228:231], v3 offset:4608
	s_waitcnt lgkmcnt(10)
	v_mfma_f32_32x32x16_bf16 v[32:47], v[188:191], v[192:195], v[32:47]
	v_exp_f32_e32 v114, v114
	v_exp_f32_e32 v115, v115
	v_exp_f32_e32 v116, v116
	ds_read_b128 v[232:235], v3 offset:6144
	s_waitcnt lgkmcnt(8)
	v_mfma_f32_32x32x16_bf16 v[48:63], v[188:191], v[196:199], v[48:63]
	v_exp_f32_e32 v117, v117
	v_exp_f32_e32 v118, v118
	v_exp_f32_e32 v119, v119
	ds_read_b128 v[240:243], v3 offset:6656
	s_waitcnt lgkmcnt(6)
	v_mfma_f32_32x32x16_bf16 v[64:79], v[188:191], v[200:203], v[64:79]
	v_exp_f32_e32 v120, v120
	v_exp_f32_e32 v121, v121
	v_exp_f32_e32 v122, v122
	v_exp_f32_e32 v123, v123
	s_waitcnt lgkmcnt(3)
	v_mfma_f32_32x32x16_bf16 v[80:95], v[188:191], v[204:207], v[80:95]
	v_exp_f32_e32 v124, v124
	v_exp_f32_e32 v125, v125
	v_exp_f32_e32 v126, v126
	v_exp_f32_e32 v127, v127
	s_mov_b32 s67, s56
	s_mov_b32 s56, s57
	s_mov_b32 s57, s58
	s_mov_b32 s58, s67
	s_add_u32 s46, s46, 1
	s_waitcnt vmcnt(3) lgkmcnt(0)
	s_barrier
	s_cmp_lg_u64 s[68:69], 0
	s_cbranch_scc0 .Lat_norescO_870
	v_lshl_add_u32 v250, v252, 4, v249
	ds_read_b128 v[0:3], v250 offset:0
	ds_read_b128 v[4:7], v250 offset:32
	ds_read_b128 v[8:11], v250 offset:64
	ds_read_b128 v[12:15], v250 offset:96
	s_nop 7
	s_nop 7
	s_waitcnt lgkmcnt(0)
	v_mul_f32_e32 v32, v32, v0
	v_mul_f32_e32 v33, v33, v1
	v_mul_f32_e32 v34, v34, v2
	v_mul_f32_e32 v35, v35, v3
	v_mul_f32_e32 v36, v36, v4
	v_mul_f32_e32 v37, v37, v5
	v_mul_f32_e32 v38, v38, v6
	v_mul_f32_e32 v39, v39, v7
	v_mul_f32_e32 v40, v40, v8
	v_mul_f32_e32 v41, v41, v9
	v_mul_f32_e32 v42, v42, v10
	v_mul_f32_e32 v43, v43, v11
	v_mul_f32_e32 v44, v44, v12
	v_mul_f32_e32 v45, v45, v13
	v_mul_f32_e32 v46, v46, v14
	v_mul_f32_e32 v47, v47, v15
	v_mul_f32_e32 v48, v48, v0
	v_mul_f32_e32 v49, v49, v1
	v_mul_f32_e32 v50, v50, v2
	v_mul_f32_e32 v51, v51, v3
	v_mul_f32_e32 v52, v52, v4
	v_mul_f32_e32 v53, v53, v5
	v_mul_f32_e32 v54, v54, v6
	v_mul_f32_e32 v55, v55, v7
	v_mul_f32_e32 v56, v56, v8
	v_mul_f32_e32 v57, v57, v9
	v_mul_f32_e32 v58, v58, v10
	v_mul_f32_e32 v59, v59, v11
	v_mul_f32_e32 v60, v60, v12
	v_mul_f32_e32 v61, v61, v13
	v_mul_f32_e32 v62, v62, v14
	v_mul_f32_e32 v63, v63, v15
	v_mul_f32_e32 v64, v64, v0
	v_mul_f32_e32 v65, v65, v1
	v_mul_f32_e32 v66, v66, v2
	v_mul_f32_e32 v67, v67, v3
	v_mul_f32_e32 v68, v68, v4
	v_mul_f32_e32 v69, v69, v5
	v_mul_f32_e32 v70, v70, v6
	v_mul_f32_e32 v71, v71, v7
	v_mul_f32_e32 v72, v72, v8
	v_mul_f32_e32 v73, v73, v9
	v_mul_f32_e32 v74, v74, v10
	v_mul_f32_e32 v75, v75, v11
	v_mul_f32_e32 v76, v76, v12
	v_mul_f32_e32 v77, v77, v13
	v_mul_f32_e32 v78, v78, v14
	v_mul_f32_e32 v79, v79, v15
	v_mul_f32_e32 v80, v80, v0
	v_mul_f32_e32 v81, v81, v1
	v_mul_f32_e32 v82, v82, v2
	v_mul_f32_e32 v83, v83, v3
	v_mul_f32_e32 v84, v84, v4
	v_mul_f32_e32 v85, v85, v5
	v_mul_f32_e32 v86, v86, v6
	v_mul_f32_e32 v87, v87, v7
	v_mul_f32_e32 v88, v88, v8
	v_mul_f32_e32 v89, v89, v9
	v_mul_f32_e32 v90, v90, v10
	v_mul_f32_e32 v91, v91, v11
	v_mul_f32_e32 v92, v92, v12
	v_mul_f32_e32 v93, v93, v13
	v_mul_f32_e32 v94, v94, v14
	v_mul_f32_e32 v95, v95, v15
